# stick-breaking loop: 0.125 scale folded into the exp constant (exact), 44 packed multiplies removed
# baseline (speedup 1.0000x reference)
; template <int LAYER>
; DI void attn_phase(const Params& p, char* smem) {
;   char* ws = p.ws;
;   bf16_t* mix = (bf16_t*)(ws + O_MIX);
;   const int xcd = (int)(blockIdx.x & 7), lb = (int)(blockIdx.x >> 3), L = (int)(gridDim.x >> 3);
;   for (int j = lb; j < 192 + 64; j += L) {
;     if (j < 192) {
;       const int hl = j >> 4, qi = j & 15, qt = ((j / L) & 1) ? (15 - qi) : qi, bh = hl * 8 + xcd, b = bh / 12, hd = bh % 12, q0 = qt * 256;
;       const size_t tok0 = (size_t)b * SEQ;
;       bf16_t* O = mix + (tok0 + q0) * DM + hd * 64;
;       if (LAYER == 0) {
;         const bf16_t* P = (const bf16_t*)(ws + O_P);
;         attn_item<64, 2, false, false>(P + (tok0 + q0) * 2560 + hd * 64, 2560, P + tok0 * 2560 + 768 + hd * 64, 2560, P + tok0 * 2560 + 1536 + hd * 64, 2560,
;                                        q0, q0 / 64 + 4, O, 0.125f, smem, nullptr, 1.f, nullptr, nullptr);
.LBB0_429:
	s_or_b64 exec, exec, s[0:1]
	s_add_u32 s0, s86, 0x71a0000
	v_writelane_b32 v254, s0, 23
	s_addc_u32 s0, s87, 0
	v_writelane_b32 v254, s0, 24
	s_waitcnt lgkmcnt(0)
	v_readlane_b32 s0, v254, 20
	s_cmpk_lt_u32 s0, 0x800
	s_cselect_b64 s[4:5], -1, 0
	v_readlane_b32 s1, v254, 21
	v_writelane_b32 v254, s4, 25
	s_cmpk_gt_u32 s0, 0x7ff
	s_barrier
	v_writelane_b32 v254, s5, 26
	v_writelane_b32 v254, s77, 27
	v_writelane_b32 v254, s92, 28
	s_nop 1
	v_writelane_b32 v254, s93, 29
	s_cbranch_scc1 .LBB0_500
	v_readlane_b32 s1, v254, 0
	v_readlane_b32 s4, v254, 2
	s_lshr_b32 s0, s1, 16
	s_and_b32 s1, s1, 0xffff
	s_and_b32 s4, 0xffff, s4
	s_lshl_b32 s16, s52, 12
	s_lshl_b32 s5, s52, 18
	s_add_u32 s33, s2, s5
	s_mul_i32 s2, s1, s4
	s_addc_u32 s57, s3, 0
	s_bfe_i32 s2, s2, 0x180000
	s_mul_i32 s0, s2, s0
	s_add_i32 s0, s0, 63
	v_bfe_u32 v1, v0, 10, 10
	v_bfe_u32 v0, v0, 20, 10
	s_andn2_b32 s0, s0, 63
	v_mad_u32_u24 v0, v0, s1, v1
	s_cmp_lg_u32 s0, 64
	v_mad_u64_u32 v[0:1], s[0:1], v0, s4, v[212:213]
	v_mbcnt_hi_u32_b32 v207, -1, v213
	v_lshrrev_b32_e32 v203, 6, v0
	v_cmp_lt_u32_e64 s[4:5], 63, v0
	v_and_b32_e32 v0, 64, v207
	s_mov_b32 s71, 0
	s_cselect_b64 s[72:73], -1, 0
	s_movk_i32 s93, 0x1400
	s_movk_i32 s12, 0xffe0
	v_mov_b32_e32 v1, 0
	s_mov_b32 s2, 0x800000
	v_mov_b32_e32 v206, 0x3c23d70a
	s_mov_b32 s75, 0x20000
	s_movk_i32 s77, 0x90
	s_movk_i32 s13, 0x110
	s_mov_b32 s56, 0xff800000
	s_mov_b32 s76, 0x3e000000
	s_mov_b32 s65, 0xbe38aa3b
	v_xor_b32_e32 v208, 32, v207
	v_add_u32_e32 v209, 64, v0
	v_mov_b32_e32 v202, 0x358637bd
	v_xor_b32_e32 v210, 1, v207
	v_xor_b32_e32 v211, 2, v207
	v_xor_b32_e32 v214, 4, v207
	v_mov_b32_e32 v215, 0xff800000
	s_mov_b32 s53, s54
	s_branch .LBB0_433

; template <int DQK, int MODE, bool QN, bool KN> ...
;     ...
;           for (int i = 0; i < 16; ++i) {
;             const float z = sacc[kb][i] * scale;
;             const float tt = __builtin_amdgcn_exp2f(-fabsf(z) * 1.4426950408889634f);
;             const float rr = __builtin_amdgcn_rcpf(1.f + tt);
;             const float trr = tt * rr;
;             float b = z >= 0.f ? rr : trr, f = z >= 0.f ? trr : rr;
;             beta[kb][i] = b; ff[kb][i] = f;
;           }
;         float cp[8], cpo[8], sp[8];
; #pragma unroll
;         for (int m = 0; m < 8; ++m) { const int kb = m >> 2, g = m & 3; cp[m] = (ff[kb][4 * g] * ff[kb][4 * g + 1]) * (ff[kb][4 * g + 2] * ff[kb][4 * g + 3]); }
; #pragma unroll
;         for (int m = 0; m < 8; ++m) {
;           const unsigned cu = __float_as_uint(cp[m]);
;           const auto rsw = __builtin_amdgcn_permlane32_swap(cu, cu, false, false);
;           cpo[m] = __uint_as_float(h == 0 ? rsw[1] : rsw[0]);
.LBB0_469:
	s_or_b64 exec, exec, s[78:79]
	v_mov_b32_e32 v14, v52
	v_mov_b32_e32 v15, v54
	v_mov_b32_e32 v54, v53
	v_mul_f32_e64 v0, |v14|, s65
	v_exp_f32_e32 v126, v0
	v_mul_f32_e64 v0, |v15|, s65
	v_exp_f32_e32 v127, v0
	v_mul_f32_e64 v53, |v54|, s65
	v_exp_f32_e32 v128, v53
	v_mul_f32_e64 v53, |v55|, s65
	v_exp_f32_e32 v129, v53
	v_add_f32_e32 v0, 1.0, v126
	v_rcp_f32_e32 v52, v0
	v_add_f32_e32 v0, 1.0, v127
	v_rcp_f32_e32 v53, v0
	v_add_f32_e32 v0, 1.0, v128
	v_rcp_f32_e32 v130, v0
	v_add_f32_e32 v0, 1.0, v129
	v_rcp_f32_e32 v131, v0
	v_pk_mul_f32 v[126:127], v[126:127], v[52:53]
	v_cmp_le_f32_e32 vcc, 0, v14
	v_cmp_le_f32_e64 s[8:9], 0, v15
	v_pk_mul_f32 v[128:129], v[128:129], v[130:131]
	v_cndmask_b32_e32 v0, v126, v52, vcc
	v_cmp_le_f32_e64 s[0:1], 0, v54
	v_cndmask_b32_e64 v154, v127, v53, s[8:9]
	v_cndmask_b32_e64 v15, v53, v127, s[8:9]
	v_cndmask_b32_e32 v14, v52, v126, vcc
	v_cmp_le_f32_e32 vcc, 0, v55
	v_mov_b32_e32 v126, v56
	v_mov_b32_e32 v127, v58
	v_cndmask_b32_e32 v53, v131, v129, vcc
	v_cndmask_b32_e64 v52, v130, v128, s[0:1]
	v_pk_mul_f32 v[54:55], v[14:15], v[52:53]
	v_mul_f32_e64 v14, |v126|, s65
	v_cndmask_b32_e64 v153, v128, v130, s[0:1]
	v_exp_f32_e32 v128, v14
	v_mul_f32_e64 v14, |v127|, s65
	v_mov_b32_e32 v58, v57
	v_cndmask_b32_e32 v155, v129, v131, vcc
	v_exp_f32_e32 v129, v14
	v_pk_mul_f32 v[54:55], v[54:55], v[54:55] op_sel:[0,1] op_sel_hi:[1,0]
	v_add_f32_e32 v14, 1.0, v128
	v_mul_f32_e64 v55, |v58|, s65
	v_exp_f32_e32 v130, v55
	v_mul_f32_e64 v55, |v59|, s65
	v_exp_f32_e32 v131, v55
	v_rcp_f32_e32 v56, v14
	v_add_f32_e32 v14, 1.0, v129
	v_rcp_f32_e32 v57, v14
	v_add_f32_e32 v14, 1.0, v130
	v_rcp_f32_e32 v132, v14
	v_add_f32_e32 v14, 1.0, v131
	v_rcp_f32_e32 v133, v14
	v_pk_mul_f32 v[128:129], v[128:129], v[56:57]
	v_cmp_le_f32_e32 vcc, 0, v126
	v_cmp_le_f32_e64 s[8:9], 0, v127
	v_pk_mul_f32 v[130:131], v[130:131], v[132:133]
	v_cndmask_b32_e32 v174, v128, v56, vcc
	v_cndmask_b32_e64 v176, v129, v57, s[8:9]
	v_cndmask_b32_e64 v57, v57, v129, s[8:9]
	v_cndmask_b32_e32 v56, v56, v128, vcc
	v_mov_b32_e32 v128, v64
	v_mov_b32_e32 v129, v66
	v_cmp_le_f32_e64 s[0:1], 0, v58
	v_cmp_le_f32_e32 vcc, 0, v59
	v_mul_f32_e64 v14, |v128|, s65
	v_mov_b32_e32 v66, v65
	v_cndmask_b32_e64 v175, v130, v132, s[0:1]
	v_cndmask_b32_e32 v59, v133, v131, vcc
	v_cndmask_b32_e64 v58, v132, v130, s[0:1]
	v_exp_f32_e32 v130, v14
	v_mul_f32_e64 v14, |v129|, s65
	v_cndmask_b32_e32 v177, v131, v133, vcc
	v_pk_mul_f32 v[126:127], v[56:57], v[58:59]
	v_exp_f32_e32 v131, v14
	v_mul_f32_e64 v56, |v66|, s65
	v_mul_f32_e32 v55, v126, v127
	v_exp_f32_e32 v126, v56
	v_mul_f32_e64 v56, |v67|, s65
	v_exp_f32_e32 v127, v56
	v_add_f32_e32 v14, 1.0, v130
	v_rcp_f32_e32 v64, v14
	v_add_f32_e32 v14, 1.0, v131
	v_rcp_f32_e32 v65, v14
	v_add_f32_e32 v14, 1.0, v126
	v_rcp_f32_e32 v132, v14
	v_add_f32_e32 v14, 1.0, v127
	v_rcp_f32_e32 v133, v14
	v_pk_mul_f32 v[130:131], v[130:131], v[64:65]
	v_cmp_le_f32_e32 vcc, 0, v128
	v_cmp_le_f32_e64 s[0:1], 0, v66
	v_pk_mul_f32 v[134:135], v[126:127], v[132:133]
	v_cndmask_b32_e32 v14, v130, v64, vcc
	v_cndmask_b32_e32 v126, v64, v130, vcc
	v_cmp_le_f32_e32 vcc, 0, v67
	v_mov_b32_e32 v66, v68
	v_mov_b32_e32 v67, v70
	v_cmp_le_f32_e64 s[8:9], 0, v129
	v_mul_f32_e64 v68, |v66|, s65
	v_exp_f32_e32 v130, v68
	v_mul_f32_e64 v68, |v67|, s65
	v_mov_b32_e32 v70, v69
	v_cndmask_b32_e64 v178, v131, v65, s[8:9]
	v_cndmask_b32_e64 v127, v65, v131, s[8:9]
	v_exp_f32_e32 v131, v68
	v_mov_b64_e32 v[68:69], v[70:71]
	v_cndmask_b32_e32 v129, v133, v135, vcc
	v_mul_f32_e64 v70, |v68|, s65
	v_exp_f32_e32 v70, v70
	v_mul_f32_e64 v71, |v69|, s65
	v_exp_f32_e32 v71, v71
	v_cndmask_b32_e64 v128, v132, v134, s[0:1]
	v_pk_mul_f32 v[64:65], v[126:127], v[128:129]
	v_cndmask_b32_e64 v56, v134, v132, s[0:1]
	v_cndmask_b32_e32 v179, v135, v133, vcc
	v_pk_mul_f32 v[134:135], v[64:65], v[64:65] op_sel:[0,1] op_sel_hi:[1,0]
	v_add_f32_e32 v64, 1.0, v130
	v_add_f32_e32 v65, 1.0, v131
	v_add_f32_e32 v124, 1.0, v70
	v_rcp_f32_e32 v64, v64
	v_rcp_f32_e32 v65, v65
	v_rcp_f32_e32 v132, v124
	v_add_f32_e32 v124, 1.0, v71
	v_rcp_f32_e32 v133, v124
	v_pk_mul_f32 v[130:131], v[130:131], v[64:65]
	v_cmp_le_f32_e32 vcc, 0, v66
	v_cmp_le_f32_e64 s[0:1], 0, v68
	v_pk_mul_f32 v[70:71], v[70:71], v[132:133]
	v_cndmask_b32_e32 v180, v130, v64, vcc
	v_cmp_le_f32_e64 s[8:9], 0, v67
	v_cndmask_b32_e32 v66, v64, v130, vcc
	v_cmp_le_f32_e32 vcc, 0, v69
	v_cndmask_b32_e64 v67, v65, v131, s[8:9]
	v_cndmask_b32_e64 v68, v132, v70, s[0:1]
	v_cndmask_b32_e32 v69, v133, v71, vcc
	v_cndmask_b32_e64 v182, v131, v65, s[8:9]
	v_pk_mul_f32 v[64:65], v[66:67], v[68:69]
	v_mov_b32_e32 v66, v54
	v_mul_f32_e32 v64, v64, v65
	v_mov_b32_e32 v65, v54
	s_nop 1
	v_permlane32_swap_b32_e32 v65, v66
	v_cndmask_b32_e64 v135, v65, v66, s[6:7]
	v_mov_b32_e32 v65, v55
	v_mov_b32_e32 v66, v55
	s_nop 1
	v_permlane32_swap_b32_e32 v65, v66
	v_cndmask_b32_e64 v181, v70, v132, s[0:1]
	v_cndmask_b32_e64 v66, v65, v66, s[6:7]
	v_mov_b32_e32 v65, v134
	v_mov_b32_e32 v70, v134
	s_nop 1
	v_permlane32_swap_b32_e32 v65, v70
	v_cndmask_b32_e64 v131, v65, v70, s[6:7]
	v_mov_b32_e32 v65, v64
	v_mov_b32_e32 v70, v64
	s_nop 1
	v_permlane32_swap_b32_e32 v65, v70
	v_cndmask_b32_e64 v124, v65, v70, s[6:7]
	v_cndmask_b32_e32 v183, v71, v133, vcc
	v_mul_f32_e32 v133, v64, v124
	v_mov_b64_e32 v[64:65], v[78:79]
	v_mul_f32_e32 v137, v55, v66
	v_mul_f32_e64 v55, |v64|, s65
	v_exp_f32_e32 v70, v55
	v_mul_f32_e64 v55, |v65|, s65
	v_exp_f32_e32 v71, v55
	v_mov_b64_e32 v[138:139], v[76:77]
	v_add_f32_e32 v55, 1.0, v70
	v_rcp_f32_e32 v78, v55
	v_add_f32_e32 v55, 1.0, v71
	v_rcp_f32_e32 v79, v55
	v_mul_f32_e64 v55, |v138|, s65
; DI unsigned pack2(float a, float b) { bf2_t v = __builtin_convertvector((f32x2){a, b}, bf2_t); return __builtin_bit_cast(unsigned, v); }
; template <int DQK, int MODE, bool QN, bool KN> ...
;     ...
;           for (int i = 0; i < 16; ++i) {
;             const float z = sacc[kb][i] * scale;
;             const float tt = __builtin_amdgcn_exp2f(-fabsf(z) * 1.4426950408889634f);
;             const float rr = __builtin_amdgcn_rcpf(1.f + tt);
;             const float trr = tt * rr;
;             float b = z >= 0.f ? rr : trr, f = z >= 0.f ? trr : rr;
;             beta[kb][i] = b; ff[kb][i] = f;
;           }
;         float cp[8], cpo[8], sp[8];
; #pragma unroll
;         for (int m = 0; m < 8; ++m) { const int kb = m >> 2, g = m & 3; cp[m] = (ff[kb][4 * g] * ff[kb][4 * g + 1]) * (ff[kb][4 * g + 2] * ff[kb][4 * g + 3]); }
; #pragma unroll
;         for (int m = 0; m < 8; ++m) {
;           const unsigned cu = __float_as_uint(cp[m]);
;           const auto rsw = __builtin_amdgcn_permlane32_swap(cu, cu, false, false);
;           cpo[m] = __uint_as_float(h == 0 ? rsw[1] : rsw[0]);
;         }
;         float run = carry;
; #pragma unroll
;         for (int m = 7; m >= 0; --m) { sp[m] = run; run *= (cp[m] * cpo[m]); }
;         carry = run;
; #pragma unroll
;         for (int m = 0; m < 8; ++m) {
;           const int kb = m >> 2, g = m & 3;
;           float tq = sp[m] * (h == 0 ? cpo[m] : 1.f);
; #pragma unroll
;           for (int c = 3; c >= 0; --c) { sacc[kb][4 * g + c] = beta[kb][4 * g + c] * tq; tq *= ff[kb][4 * g + c]; }
;     ...
; #pragma unroll
;       for (int kb = 0; kb < 2; ++kb)
; #pragma unroll
;         for (int s2 = 0; s2 < 2; ++s2) {
;           u32x4 pw;
;           pw.x = pack2(sacc[kb][8 * s2 + 0], sacc[kb][8 * s2 + 1]); pw.y = pack2(sacc[kb][8 * s2 + 2], sacc[kb][8 * s2 + 3]);
;           pw.z = pack2(sacc[kb][8 * s2 + 4], sacc[kb][8 * s2 + 5]); pw.w = pack2(sacc[kb][8 * s2 + 6], sacc[kb][8 * s2 + 7]);
;           const bf16x8 pf = __builtin_bit_cast(bf16x8, pw);
; #pragma unroll
;           for (int dvb = 0; dvb < 2; ++dvb) {
;             const char* vb = sV + dvb * VIMG + (kb * 32 + 16 * s2) * 64 + vtr_off;
;             const s16x4 v0 = tr_read(vb), v1 = tr_read(vb + 8 * 64);
;             const bf16x8 vf = __builtin_shufflevector(v0, v1, 0, 1, 2, 3, 4, 5, 6, 7);
	v_exp_f32_e32 v156, v55
	v_mul_f32_e64 v55, |v139|, s65
	v_exp_f32_e32 v157, v55
	v_add_f32_e32 v55, 1.0, v156
	v_rcp_f32_e32 v158, v55
	v_add_f32_e32 v55, 1.0, v157
	v_rcp_f32_e32 v159, v55
	v_pk_mul_f32 v[70:71], v[70:71], v[78:79]
	v_cmp_le_f32_e32 vcc, 0, v65
	v_cmp_le_f32_e64 s[0:1], 0, v64
	v_mul_f32_e64 v55, |v74|, s65
	v_cndmask_b32_e32 v65, v71, v79, vcc
	v_cndmask_b32_e64 v64, v70, v78, s[0:1]
	v_cndmask_b32_e32 v186, v79, v71, vcc
	v_cndmask_b32_e64 v187, v78, v70, s[0:1]
	v_pk_mul_f32 v[78:79], v[156:157], v[158:159]
	v_exp_f32_e32 v156, v55
	v_mul_f32_e64 v55, |v75|, s65
	v_exp_f32_e32 v157, v55
	v_cmp_le_f32_e32 vcc, 0, v139
	v_add_f32_e32 v55, 1.0, v156
	v_cmp_le_f32_e64 s[0:1], 0, v138
	v_rcp_f32_e32 v138, v55
	v_add_f32_e32 v55, 1.0, v157
	v_rcp_f32_e32 v139, v55
	v_cndmask_b32_e32 v188, v159, v79, vcc
	v_cndmask_b32_e64 v55, v158, v78, s[0:1]
	v_mov_b64_e32 v[160:161], v[72:73]
	v_cndmask_b32_e32 v71, v79, v159, vcc
	v_mul_f32_e32 v159, v55, v188
	v_mul_f32_e64 v55, |v160|, s65
	v_exp_f32_e32 v162, v55
	v_mul_f32_e64 v55, |v161|, s65
	v_exp_f32_e32 v163, v55
	v_cndmask_b32_e64 v70, v78, v158, s[0:1]
	v_add_f32_e32 v55, 1.0, v162
	v_rcp_f32_e32 v164, v55
	v_add_f32_e32 v55, 1.0, v163
	v_rcp_f32_e32 v165, v55
	v_pk_mul_f32 v[156:157], v[156:157], v[138:139]
	v_cmp_le_f32_e32 vcc, 0, v75
	v_cmp_le_f32_e64 s[0:1], 0, v74
	v_mul_f32_e32 v77, v187, v186
	v_cndmask_b32_e32 v79, v157, v139, vcc
	v_cndmask_b32_e64 v78, v156, v138, s[0:1]
	v_cndmask_b32_e32 v189, v139, v157, vcc
	v_cndmask_b32_e64 v190, v138, v156, s[0:1]
	v_pk_mul_f32 v[138:139], v[162:163], v[164:165]
	v_cmp_le_f32_e32 vcc, 0, v160
	v_cmp_le_f32_e64 s[0:1], 0, v161
	v_mul_f32_e32 v72, v190, v189
	v_cndmask_b32_e32 v158, v164, v138, vcc
	v_cndmask_b32_e64 v76, v165, v139, s[0:1]
	v_cndmask_b32_e64 v75, v139, v165, s[0:1]
	v_cndmask_b32_e32 v74, v138, v164, vcc
	v_pk_mul_f32 v[138:139], v[158:159], v[76:77]
	v_mov_b64_e32 v[156:157], v[62:63]
	v_mov_b32_e32 v55, v139
	v_mov_b32_e32 v73, v139
	s_nop 1
	v_permlane32_swap_b32_e32 v55, v73
	v_cndmask_b32_e64 v73, v55, v73, s[6:7]
	v_pk_mul_f32 v[138:139], v[138:139], v[72:73]
	v_mul_f32_e64 v62, |v156|, s65
	v_mov_b32_e32 v55, v138
	v_mov_b32_e32 v72, v138
	s_nop 1
	v_permlane32_swap_b32_e32 v55, v72
	v_cndmask_b32_e64 v185, 1.0, v124, s[6:7]
	v_exp_f32_e32 v158, v62
	v_mul_f32_e64 v62, |v157|, s65
	v_cndmask_b32_e64 v124, v55, v72, s[6:7]
	v_mul_f32_e64 v55, |v60|, s65
	v_exp_f32_e32 v159, v62
	v_exp_f32_e32 v162, v55
	v_mul_f32_e64 v55, |v61|, s65
	v_exp_f32_e32 v163, v55
	v_add_f32_e32 v62, 1.0, v158
	v_rcp_f32_e32 v160, v62
	v_add_f32_e32 v62, 1.0, v159
	v_add_f32_e32 v55, 1.0, v162
	v_rcp_f32_e32 v161, v62
	v_rcp_f32_e32 v164, v55
	v_add_f32_e32 v55, 1.0, v163
	v_rcp_f32_e32 v165, v55
	v_pk_mul_f32 v[158:159], v[158:159], v[160:161]
	v_cmp_le_f32_e32 vcc, 0, v156
	v_cmp_le_f32_e64 s[0:1], 0, v157
	v_cndmask_b32_e32 v132, v160, v158, vcc
	v_cndmask_b32_e32 v156, v158, v160, vcc
	v_pk_mul_f32 v[162:163], v[162:163], v[164:165]
	v_cmp_le_f32_e32 vcc, 0, v60
	v_mul_f32_e64 v72, |v50|, s65
	v_cndmask_b32_e64 v157, v159, v161, s[0:1]
	v_cndmask_b32_e64 v158, v161, v159, s[0:1]
	v_cndmask_b32_e32 v60, v164, v162, vcc
	v_cmp_le_f32_e64 s[0:1], 0, v61
	v_cndmask_b32_e32 v166, v162, v164, vcc
	v_exp_f32_e32 v162, v72
	v_mul_f32_e64 v72, |v51|, s65
	v_cmp_le_f32_e32 vcc, 0, v50
	v_mul_f32_e64 v50, |v48|, s65
	v_cndmask_b32_e64 v167, v163, v165, s[0:1]
	v_cndmask_b32_e64 v130, v165, v163, s[0:1]
	v_exp_f32_e32 v163, v72
	v_exp_f32_e32 v170, v50
	v_mul_f32_e64 v50, |v49|, s65
	v_exp_f32_e32 v171, v50
	v_pk_mul_f32 v[62:63], v[138:139], v[124:125]
	v_add_f32_e32 v72, 1.0, v162
	v_pk_mul_f32 v[138:139], v[62:63], v[62:63] op_sel:[0,1] op_sel_hi:[1,0]
	v_mov_b32_e32 v61, v134
	v_mov_b32_e32 v159, v138
	v_rcp_f32_e32 v164, v72
	v_add_f32_e32 v72, 1.0, v163
	v_add_f32_e32 v50, 1.0, v170
	v_pk_mul_f32 v[160:161], v[132:133], v[158:159]
	v_pk_mul_f32 v[60:61], v[60:61], v[130:131]
	v_rcp_f32_e32 v165, v72
	v_rcp_f32_e32 v172, v50
	v_add_f32_e32 v50, 1.0, v171
	v_pk_mul_f32 v[60:61], v[60:61], v[160:161]
	v_rcp_f32_e32 v173, v50
	v_mov_b32_e32 v55, v60
	v_mov_b32_e32 v62, v60
	s_nop 1
	v_permlane32_swap_b32_e32 v55, v62
	v_cndmask_b32_e64 v62, v55, v62, s[6:7]
	v_pk_mul_f32 v[162:163], v[162:163], v[164:165]
	v_cmp_le_f32_e64 s[0:1], 0, v51
	v_mul_f32_e32 v55, v60, v62
	v_cndmask_b32_e32 v136, v164, v162, vcc
	v_cndmask_b32_e64 v51, v163, v165, s[0:1]
	v_cndmask_b32_e32 v50, v162, v164, vcc
	v_cndmask_b32_e64 v168, v165, v163, s[0:1]
	v_pk_mul_f32 v[164:165], v[170:171], v[172:173]
	v_cmp_le_f32_e32 vcc, 0, v48
	v_cmp_le_f32_e64 s[0:1], 0, v49
	v_mul_f32_e32 v169, v55, v61
	v_cndmask_b32_e32 v48, v172, v164, vcc
	v_cndmask_b32_e64 v134, v173, v165, s[0:1]
	v_mov_b32_e32 v49, v54
	v_pk_mul_f32 v[162:163], v[136:137], v[168:169]
	v_pk_mul_f32 v[48:49], v[48:49], v[134:135]
	v_cndmask_b32_e64 v171, v165, v173, s[0:1]
	v_cndmask_b32_e32 v170, v164, v172, vcc
	v_pk_mul_f32 v[164:165], v[48:49], v[162:163]
	v_cndmask_b32_e64 v126, 1.0, v135, s[6:7]
	v_mov_b32_e32 v48, v164
	v_mov_b32_e32 v49, v164
	s_nop 1
	v_permlane32_swap_b32_e32 v48, v49
	v_cndmask_b32_e64 v72, v48, v49, s[6:7]
	v_cndmask_b32_e64 v48, 1.0, v72, s[6:7]
	v_mul_f32_e32 v49, v48, v165
	v_mul_f32_e32 v48, v168, v49
	v_pk_mul_f32 v[54:55], v[50:51], v[48:49]
	v_mul_f32_e32 v49, v136, v48
	v_mul_f32_e32 v48, v134, v49
	v_pk_mul_f32 v[134:135], v[170:171], v[48:49]
	v_mul_f32_e32 v48, v126, v163
	v_mul_f32_e32 v77, v155, v48
	v_mul_f32_e32 v48, v53, v48
	v_mul_f32_e32 v126, v154, v48
	v_mul_f32_e32 v15, v15, v48
	v_cndmask_b32_e64 v48, 1.0, v62, s[6:7]
	v_mul_f32_e32 v49, v48, v61
	v_mul_f32_e32 v48, v158, v49
	v_pk_mul_f32 v[60:61], v[156:157], v[48:49]
	v_mul_f32_e32 v49, v132, v48
	v_cndmask_b32_e64 v184, 1.0, v131, s[6:7]
	v_mul_f32_e32 v48, v130, v49
	v_pk_mul_f32 v[130:131], v[166:167], v[48:49]
	v_mul_f32_e32 v48, v184, v161
	v_cndmask_b32_e64 v66, 1.0, v66, s[6:7]
	v_mul_f32_e32 v133, v153, v15
	v_mul_f32_e32 v15, v52, v15
	v_mul_f32_e32 v62, v179, v48
	v_mul_f32_e32 v48, v129, v48
	v_mul_f32_e32 v0, v0, v15
	v_mul_f32_e32 v15, v66, v169
	v_mul_f32_e32 v132, v178, v48
	v_mul_f32_e32 v48, v127, v48
	v_lshl_add_u32 v154, s66, 6, v152
	v_mul_f32_e32 v66, v177, v15
	v_mul_f32_e32 v15, v59, v15
	v_mul_f32_e32 v139, v56, v48
	v_mul_f32_e32 v153, v128, v48
	ds_read_b64_tr_b16 v[48:49], v154 offset:18432
	ds_read_b64_tr_b16 v[50:51], v154 offset:18944
	v_mul_f32_e32 v136, v176, v15
	v_mul_f32_e32 v15, v57, v15
	v_mul_f32_e32 v137, v175, v15
	v_mul_f32_e32 v15, v58, v15
	v_cvt_pk_bf16_f32 v53, v54, v55
	v_cvt_pk_bf16_f32 v55, v126, v77
	ds_read_b64_tr_b16 v[56:57], v154 offset:26624
	ds_read_b64_tr_b16 v[58:59], v154 offset:27136
	ds_read_b64_tr_b16 v[126:127], v154 offset:19456
	ds_read_b64_tr_b16 v[128:129], v154 offset:19968
	v_cvt_pk_bf16_f32 v52, v134, v135
	v_cvt_pk_bf16_f32 v54, v0, v133
	v_mul_f32_e32 v15, v174, v15
	v_mul_f32_e32 v0, v14, v153
	s_waitcnt lgkmcnt(4)
; template <int DQK, int MODE, bool QN, bool KN> ...
;     ...
;         for (int m = 0; m < 8; ++m) {
;           const int kb = m >> 2, g = m & 3;
;           float tq = sp[m] * (h == 0 ? cpo[m] : 1.f);
; #pragma unroll
;           for (int c = 3; c >= 0; --c) { sacc[kb][4 * g + c] = beta[kb][4 * g + c] * tq; tq *= ff[kb][4 * g + c]; }
;         }
;       } else if (fixed_shift) {
;         float ps = 0.f;
; #pragma unroll
;         for (int kb = 0; kb < 2; ++kb)
; #pragma unroll
;           for (int i = 0; i < 16; ++i) { const float pv = __builtin_amdgcn_exp2f(sacc[kb][i]); sacc[kb][i] = pv; ps += pv; }
;         l_run += ps;
;       } else {
;         float tmax = -INFINITY;
; #pragma unroll
;         for (int kb = 0; kb < 2; ++kb)
; #pragma unroll
;           for (int i = 0; i < 16; ++i) {
;             tmax = fmaxf(tmax, sacc[kb][i]);
;           }
;         tmax = fmaxf(tmax, __shfl_xor(tmax, 32));
;         const float m_new = fmaxf(m_run, tmax);
;         const float alpha = __builtin_amdgcn_exp2f(m_run - m_new);
;         m_run = m_new;
;         float ps = 0.f;
; #pragma unroll
;         for (int kb = 0; kb < 2; ++kb)
; #pragma unroll
;           for (int i = 0; i < 16; ++i) { const float pv = __builtin_amdgcn_exp2f(sacc[kb][i] - m_new); sacc[kb][i] = pv; ps += pv; }
;         l_run = l_run * alpha + ps;
;         if (__builtin_amdgcn_ballot_w64(alpha != 1.f) != 0) {
; #pragma unroll
;           for (int a = 0; a < 2; ++a)
; #pragma unroll
;             for (int i = 0; i < 16; ++i) o[a][i] *= alpha;
;         }
;       }
; #pragma unroll
;       for (int kb = 0; kb < 2; ++kb)
; #pragma unroll
;         for (int s2 = 0; s2 < 2; ++s2) {
;           u32x4 pw;
;           pw.x = pack2(sacc[kb][8 * s2 + 0], sacc[kb][8 * s2 + 1]); pw.y = pack2(sacc[kb][8 * s2 + 2], sacc[kb][8 * s2 + 3]);
;           pw.z = pack2(sacc[kb][8 * s2 + 4], sacc[kb][8 * s2 + 5]); pw.w = pack2(sacc[kb][8 * s2 + 6], sacc[kb][8 * s2 + 7]);
;           const bf16x8 pf = __builtin_bit_cast(bf16x8, pw);
; #pragma unroll
;           for (int dvb = 0; dvb < 2; ++dvb) {
;             const char* vb = sV + dvb * VIMG + (kb * 32 + 16 * s2) * 64 + vtr_off;
;             const s16x4 v0 = tr_read(vb), v1 = tr_read(vb + 8 * 64);
;             const bf16x8 vf = __builtin_shufflevector(v0, v1, 0, 1, 2, 3, 4, 5, 6, 7);
;             o[dvb] = MFMA32(vf, pf, o[dvb]);
;           }
	v_mfma_f32_32x32x16_bf16 v[32:47], v[48:51], v[52:55], v[32:47]
	ds_read_b64_tr_b16 v[48:49], v154 offset:27648
	ds_read_b64_tr_b16 v[50:51], v154 offset:28160
	v_mul_f32_e32 v14, v185, v138
	v_mul_f32_e32 v77, v183, v14
	v_mul_f32_e32 v14, v69, v14
	v_mul_f32_e32 v69, v182, v14
	v_mul_f32_e32 v14, v67, v14
	s_waitcnt lgkmcnt(4)
	v_mfma_f32_32x32x16_bf16 v[16:31], v[56:59], v[52:55], v[16:31]
	v_cvt_pk_bf16_f32 v52, v15, v137
	v_cvt_pk_bf16_f32 v53, v136, v66
	v_cvt_pk_bf16_f32 v54, v130, v131
	v_cvt_pk_bf16_f32 v55, v60, v61
	v_mul_f32_e32 v56, v181, v14
	v_mul_f32_e32 v14, v68, v14
	v_mul_f32_e32 v57, v180, v14
	s_waitcnt lgkmcnt(2)
	v_mfma_f32_32x32x16_bf16 v[32:47], v[126:129], v[52:55], v[32:47]
	v_cndmask_b32_e64 v14, 1.0, v124, s[6:7]
	v_mul_f32_e32 v15, v14, v63
	v_mul_f32_e32 v14, v189, v15
	v_mul_f32_e64 v66, v78, v14
	v_mul_f32_e64 v67, v79, v15
	v_mul_f32_e32 v15, v190, v14
	v_mul_f32_e32 v14, v76, v15
	v_pk_mul_f32 v[14:15], v[74:75], v[14:15]
	s_waitcnt lgkmcnt(0)
	v_mfma_f32_32x32x16_bf16 v[16:31], v[48:51], v[52:55], v[16:31]
	ds_read_b64_tr_b16 v[48:49], v154 offset:20480
	ds_read_b64_tr_b16 v[50:51], v154 offset:20992
	v_cvt_pk_bf16_f32 v53, v132, v62
	v_cvt_pk_bf16_f32 v54, v57, v56
	ds_read_b64_tr_b16 v[56:57], v154 offset:28672
	ds_read_b64_tr_b16 v[58:59], v154 offset:29184
	ds_read_b64_tr_b16 v[60:61], v154 offset:21504
	ds_read_b64_tr_b16 v[62:63], v154 offset:22016
	v_cvt_pk_bf16_f32 v52, v0, v139
	v_cvt_pk_bf16_f32 v55, v69, v77
	v_cndmask_b32_e64 v0, 1.0, v73, s[6:7]
	v_mul_f32_e32 v69, v125, v0
	s_waitcnt lgkmcnt(4)
	v_mfma_f32_32x32x16_bf16 v[32:47], v[48:51], v[52:55], v[32:47]
	v_mul_f32_e32 v68, v186, v69
	ds_read_b64_tr_b16 v[48:49], v154 offset:29696
	ds_read_b64_tr_b16 v[50:51], v154 offset:30208
	v_mul_f32_e64 v64, v64, v68
	v_mul_f32_e64 v65, v65, v69
	v_mul_f32_e32 v0, v164, v72
	v_mul_f32_e32 v125, v0, v165
	s_waitcnt lgkmcnt(4)
	v_mfma_f32_32x32x16_bf16 v[16:31], v[56:59], v[52:55], v[16:31]
	v_mul_f32_e32 v53, v187, v68
	v_mul_f32_e32 v52, v188, v53
	v_mul_f32_e64 v54, v70, v52
	v_mul_f32_e64 v55, v71, v53
	v_cvt_pk_bf16_f32 v52, v14, v15
	v_cvt_pk_bf16_f32 v53, v66, v67
	v_cvt_pk_bf16_f32 v54, v54, v55
	v_cvt_pk_bf16_f32 v55, v64, v65
	s_waitcnt lgkmcnt(2)
	s_nop 0
	v_mfma_f32_32x32x16_bf16 v[32:47], v[60:63], v[52:55], v[32:47]
	s_waitcnt lgkmcnt(0)
	v_mfma_f32_32x32x16_bf16 v[16:31], v[48:51], v[52:55], v[16:31]

; template <int DQK, int MODE, bool QN, bool KN> ...
;     ...
;           for (int i = 0; i < 16; ++i) {
;             const float z = sacc[kb][i] * scale;
;             const float tt = __builtin_amdgcn_exp2f(-fabsf(z) * 1.4426950408889634f);
;             const float rr = __builtin_amdgcn_rcpf(1.f + tt);
;             const float trr = tt * rr;
;             float b = z >= 0.f ? rr : trr, f = z >= 0.f ? trr : rr;
;             beta[kb][i] = b; ff[kb][i] = f;
;           }
;         float cp[8], cpo[8], sp[8];
; #pragma unroll
;         for (int m = 0; m < 8; ++m) { const int kb = m >> 2, g = m & 3; cp[m] = (ff[kb][4 * g] * ff[kb][4 * g + 1]) * (ff[kb][4 * g + 2] * ff[kb][4 * g + 3]); }
; #pragma unroll
;         for (int m = 0; m < 8; ++m) {
;           const unsigned cu = __float_as_uint(cp[m]);
;           const auto rsw = __builtin_amdgcn_permlane32_swap(cu, cu, false, false);
;           cpo[m] = __uint_as_float(h == 0 ? rsw[1] : rsw[0]);
;         }
.LBB0_485:
	s_or_b64 exec, exec, s[66:67]
	v_mov_b32_e32 v14, v52
	v_mov_b32_e32 v15, v54
	v_mov_b32_e32 v54, v53
	v_mul_f32_e64 v0, |v14|, s65
	v_exp_f32_e32 v126, v0
	v_mul_f32_e64 v0, |v15|, s65
	v_exp_f32_e32 v127, v0
	v_mul_f32_e64 v53, |v54|, s65
	v_exp_f32_e32 v128, v53
	v_mul_f32_e64 v53, |v55|, s65
	v_exp_f32_e32 v129, v53
	v_add_f32_e32 v0, 1.0, v126
	v_rcp_f32_e32 v52, v0
	v_add_f32_e32 v0, 1.0, v127
	v_rcp_f32_e32 v53, v0
	v_add_f32_e32 v0, 1.0, v128
	v_rcp_f32_e32 v130, v0
	v_add_f32_e32 v0, 1.0, v129
	v_rcp_f32_e32 v131, v0
	v_pk_mul_f32 v[126:127], v[126:127], v[52:53]
	v_cmp_le_f32_e32 vcc, 0, v14
	v_cmp_le_f32_e64 s[10:11], 0, v15
	v_pk_mul_f32 v[128:129], v[128:129], v[130:131]
	v_cndmask_b32_e32 v0, v126, v52, vcc
	v_cmp_le_f32_e64 s[0:1], 0, v54
	v_cndmask_b32_e64 v154, v127, v53, s[10:11]
	v_cndmask_b32_e64 v15, v53, v127, s[10:11]
	v_cndmask_b32_e32 v14, v52, v126, vcc
	v_cmp_le_f32_e32 vcc, 0, v55
	v_mov_b32_e32 v126, v56
	v_mov_b32_e32 v127, v58
	v_cndmask_b32_e32 v53, v131, v129, vcc
	v_cndmask_b32_e64 v52, v130, v128, s[0:1]
	v_pk_mul_f32 v[54:55], v[14:15], v[52:53]
	v_mul_f32_e64 v14, |v126|, s65
	v_cndmask_b32_e64 v153, v128, v130, s[0:1]
	v_exp_f32_e32 v128, v14
	v_mul_f32_e64 v14, |v127|, s65
	v_mov_b32_e32 v58, v57
	v_cndmask_b32_e32 v155, v129, v131, vcc
	v_exp_f32_e32 v129, v14
	v_pk_mul_f32 v[54:55], v[54:55], v[54:55] op_sel:[0,1] op_sel_hi:[1,0]
	v_add_f32_e32 v14, 1.0, v128
	v_mul_f32_e64 v55, |v58|, s65
	v_exp_f32_e32 v130, v55
	v_mul_f32_e64 v55, |v59|, s65
	v_exp_f32_e32 v131, v55
	v_rcp_f32_e32 v56, v14
	v_add_f32_e32 v14, 1.0, v129
	v_rcp_f32_e32 v57, v14
	v_add_f32_e32 v14, 1.0, v130
	v_rcp_f32_e32 v132, v14
	v_add_f32_e32 v14, 1.0, v131
	v_rcp_f32_e32 v133, v14
	v_pk_mul_f32 v[128:129], v[128:129], v[56:57]
	v_cmp_le_f32_e32 vcc, 0, v126
	v_cmp_le_f32_e64 s[10:11], 0, v127
	v_pk_mul_f32 v[130:131], v[130:131], v[132:133]
	v_cndmask_b32_e32 v174, v128, v56, vcc
	v_cndmask_b32_e64 v176, v129, v57, s[10:11]
	v_cndmask_b32_e64 v57, v57, v129, s[10:11]
	v_cndmask_b32_e32 v56, v56, v128, vcc
	v_mov_b32_e32 v128, v64
	v_mov_b32_e32 v129, v66
	v_cmp_le_f32_e64 s[0:1], 0, v58
	v_cmp_le_f32_e32 vcc, 0, v59
	v_mul_f32_e64 v14, |v128|, s65
	v_mov_b32_e32 v66, v65
	v_cndmask_b32_e64 v175, v130, v132, s[0:1]
	v_cndmask_b32_e32 v59, v133, v131, vcc
	v_cndmask_b32_e64 v58, v132, v130, s[0:1]
	v_exp_f32_e32 v130, v14
	v_mul_f32_e64 v14, |v129|, s65
	v_cndmask_b32_e32 v177, v131, v133, vcc
	v_pk_mul_f32 v[126:127], v[56:57], v[58:59]
	v_exp_f32_e32 v131, v14
	v_mul_f32_e64 v56, |v66|, s65
	v_mul_f32_e32 v55, v126, v127
	v_exp_f32_e32 v126, v56
	v_mul_f32_e64 v56, |v67|, s65
	v_exp_f32_e32 v127, v56
	v_add_f32_e32 v14, 1.0, v130
	v_rcp_f32_e32 v64, v14
	v_add_f32_e32 v14, 1.0, v131
	v_rcp_f32_e32 v65, v14
	v_add_f32_e32 v14, 1.0, v126
	v_rcp_f32_e32 v132, v14
	v_add_f32_e32 v14, 1.0, v127
	v_rcp_f32_e32 v133, v14
	v_pk_mul_f32 v[130:131], v[130:131], v[64:65]
	v_cmp_le_f32_e32 vcc, 0, v128
	v_cmp_le_f32_e64 s[0:1], 0, v66
	v_pk_mul_f32 v[134:135], v[126:127], v[132:133]
	v_cndmask_b32_e32 v14, v130, v64, vcc
	v_cndmask_b32_e32 v126, v64, v130, vcc
	v_cmp_le_f32_e32 vcc, 0, v67
	v_mov_b32_e32 v66, v68
	v_mov_b32_e32 v67, v70
	v_cmp_le_f32_e64 s[10:11], 0, v129
	v_mul_f32_e64 v68, |v66|, s65
	v_exp_f32_e32 v130, v68
	v_mul_f32_e64 v68, |v67|, s65
	v_mov_b32_e32 v70, v69
	v_cndmask_b32_e64 v178, v131, v65, s[10:11]
	v_cndmask_b32_e64 v127, v65, v131, s[10:11]
	v_exp_f32_e32 v131, v68
	v_mov_b64_e32 v[68:69], v[70:71]
	v_cndmask_b32_e32 v129, v133, v135, vcc
	v_mul_f32_e64 v70, |v68|, s65
	v_exp_f32_e32 v70, v70
	v_mul_f32_e64 v71, |v69|, s65
	v_exp_f32_e32 v71, v71
	v_cndmask_b32_e64 v128, v132, v134, s[0:1]
	v_pk_mul_f32 v[64:65], v[126:127], v[128:129]
	v_cndmask_b32_e64 v56, v134, v132, s[0:1]
	v_cndmask_b32_e32 v179, v135, v133, vcc
	v_pk_mul_f32 v[134:135], v[64:65], v[64:65] op_sel:[0,1] op_sel_hi:[1,0]
	v_add_f32_e32 v64, 1.0, v130
	v_add_f32_e32 v65, 1.0, v131
	v_add_f32_e32 v124, 1.0, v70
	v_rcp_f32_e32 v64, v64
	v_rcp_f32_e32 v65, v65
	v_rcp_f32_e32 v132, v124
	v_add_f32_e32 v124, 1.0, v71
	v_rcp_f32_e32 v133, v124
	v_pk_mul_f32 v[130:131], v[130:131], v[64:65]
	v_cmp_le_f32_e32 vcc, 0, v66
	v_cmp_le_f32_e64 s[0:1], 0, v68
	v_pk_mul_f32 v[70:71], v[70:71], v[132:133]
	v_cndmask_b32_e32 v180, v130, v64, vcc
	v_cmp_le_f32_e64 s[10:11], 0, v67
	v_cndmask_b32_e32 v66, v64, v130, vcc
	v_cmp_le_f32_e32 vcc, 0, v69
	v_cndmask_b32_e64 v67, v65, v131, s[10:11]
	v_cndmask_b32_e64 v68, v132, v70, s[0:1]
	v_cndmask_b32_e32 v69, v133, v71, vcc
	v_cndmask_b32_e64 v182, v131, v65, s[10:11]
	v_pk_mul_f32 v[64:65], v[66:67], v[68:69]
	v_mov_b32_e32 v66, v54
	v_mul_f32_e32 v64, v64, v65
	v_mov_b32_e32 v65, v54
	s_nop 1
	v_permlane32_swap_b32_e32 v65, v66
	v_cndmask_b32_e64 v135, v65, v66, s[6:7]
	v_mov_b32_e32 v65, v55
	v_mov_b32_e32 v66, v55
	s_nop 1
	v_permlane32_swap_b32_e32 v65, v66
	v_cndmask_b32_e64 v181, v70, v132, s[0:1]
	v_cndmask_b32_e64 v66, v65, v66, s[6:7]
	v_mov_b32_e32 v65, v134
	v_mov_b32_e32 v70, v134
	s_nop 1
	v_permlane32_swap_b32_e32 v65, v70
	v_cndmask_b32_e64 v131, v65, v70, s[6:7]
	v_mov_b32_e32 v65, v64
	v_mov_b32_e32 v70, v64
	s_nop 1
	v_permlane32_swap_b32_e32 v65, v70
	v_cndmask_b32_e64 v124, v65, v70, s[6:7]
	v_cndmask_b32_e32 v183, v71, v133, vcc
	v_mul_f32_e32 v133, v64, v124
	v_mov_b64_e32 v[64:65], v[78:79]
	v_mul_f32_e32 v137, v55, v66
	v_mul_f32_e64 v55, |v64|, s65
	v_exp_f32_e32 v70, v55
	v_mul_f32_e64 v55, |v65|, s65
	v_exp_f32_e32 v71, v55
	v_mov_b64_e32 v[138:139], v[76:77]
	v_add_f32_e32 v55, 1.0, v70
	v_rcp_f32_e32 v78, v55
	v_add_f32_e32 v55, 1.0, v71
	v_rcp_f32_e32 v79, v55
; DI unsigned pack2(float a, float b) { bf2_t v = __builtin_convertvector((f32x2){a, b}, bf2_t); return __builtin_bit_cast(unsigned, v); }
; template <int DQK, int MODE, bool QN, bool KN> ...
;     ...
;           for (int i = 0; i < 16; ++i) {
;             const float z = sacc[kb][i] * scale;
;             const float tt = __builtin_amdgcn_exp2f(-fabsf(z) * 1.4426950408889634f);
;             const float rr = __builtin_amdgcn_rcpf(1.f + tt);
;             const float trr = tt * rr;
;             float b = z >= 0.f ? rr : trr, f = z >= 0.f ? trr : rr;
;             beta[kb][i] = b; ff[kb][i] = f;
;           }
;         float cp[8], cpo[8], sp[8];
; #pragma unroll
;         for (int m = 0; m < 8; ++m) { const int kb = m >> 2, g = m & 3; cp[m] = (ff[kb][4 * g] * ff[kb][4 * g + 1]) * (ff[kb][4 * g + 2] * ff[kb][4 * g + 3]); }
; #pragma unroll
;         for (int m = 0; m < 8; ++m) {
;           const unsigned cu = __float_as_uint(cp[m]);
;           const auto rsw = __builtin_amdgcn_permlane32_swap(cu, cu, false, false);
;           cpo[m] = __uint_as_float(h == 0 ? rsw[1] : rsw[0]);
;         }
;         float run = carry;
; #pragma unroll
;         for (int m = 7; m >= 0; --m) { sp[m] = run; run *= (cp[m] * cpo[m]); }
;         carry = run;
; #pragma unroll
;         for (int m = 0; m < 8; ++m) {
;           const int kb = m >> 2, g = m & 3;
;           float tq = sp[m] * (h == 0 ? cpo[m] : 1.f);
; #pragma unroll
;           for (int c = 3; c >= 0; --c) { sacc[kb][4 * g + c] = beta[kb][4 * g + c] * tq; tq *= ff[kb][4 * g + c]; }
;     ...
; #pragma unroll
;       for (int kb = 0; kb < 2; ++kb)
; #pragma unroll
;         for (int s2 = 0; s2 < 2; ++s2) {
;           u32x4 pw;
;           pw.x = pack2(sacc[kb][8 * s2 + 0], sacc[kb][8 * s2 + 1]); pw.y = pack2(sacc[kb][8 * s2 + 2], sacc[kb][8 * s2 + 3]);
;           pw.z = pack2(sacc[kb][8 * s2 + 4], sacc[kb][8 * s2 + 5]); pw.w = pack2(sacc[kb][8 * s2 + 6], sacc[kb][8 * s2 + 7]);
;           const bf16x8 pf = __builtin_bit_cast(bf16x8, pw);
; #pragma unroll
;           for (int dvb = 0; dvb < 2; ++dvb) {
;             const char* vb = sV + dvb * VIMG + (kb * 32 + 16 * s2) * 64 + vtr_off;
;             const s16x4 v0 = tr_read(vb), v1 = tr_read(vb + 8 * 64);
;             const bf16x8 vf = __builtin_shufflevector(v0, v1, 0, 1, 2, 3, 4, 5, 6, 7);
	v_mul_f32_e64 v55, |v138|, s65
	v_exp_f32_e32 v156, v55
	v_mul_f32_e64 v55, |v139|, s65
	v_exp_f32_e32 v157, v55
	v_add_f32_e32 v55, 1.0, v156
	v_rcp_f32_e32 v158, v55
	v_add_f32_e32 v55, 1.0, v157
	v_rcp_f32_e32 v159, v55
	v_pk_mul_f32 v[70:71], v[70:71], v[78:79]
	v_cmp_le_f32_e32 vcc, 0, v65
	v_cmp_le_f32_e64 s[0:1], 0, v64
	v_mul_f32_e64 v55, |v74|, s65
	v_cndmask_b32_e32 v65, v71, v79, vcc
	v_cndmask_b32_e64 v64, v70, v78, s[0:1]
	v_cndmask_b32_e32 v186, v79, v71, vcc
	v_cndmask_b32_e64 v187, v78, v70, s[0:1]
	v_pk_mul_f32 v[78:79], v[156:157], v[158:159]
	v_exp_f32_e32 v156, v55
	v_mul_f32_e64 v55, |v75|, s65
	v_exp_f32_e32 v157, v55
	v_cmp_le_f32_e32 vcc, 0, v139
	v_add_f32_e32 v55, 1.0, v156
	v_cmp_le_f32_e64 s[0:1], 0, v138
	v_rcp_f32_e32 v138, v55
	v_add_f32_e32 v55, 1.0, v157
	v_rcp_f32_e32 v139, v55
	v_cndmask_b32_e32 v188, v159, v79, vcc
	v_cndmask_b32_e64 v55, v158, v78, s[0:1]
	v_mov_b64_e32 v[160:161], v[72:73]
	v_cndmask_b32_e32 v71, v79, v159, vcc
	v_mul_f32_e32 v159, v55, v188
	v_mul_f32_e64 v55, |v160|, s65
	v_exp_f32_e32 v162, v55
	v_mul_f32_e64 v55, |v161|, s65
	v_exp_f32_e32 v163, v55
	v_cndmask_b32_e64 v70, v78, v158, s[0:1]
	v_add_f32_e32 v55, 1.0, v162
	v_rcp_f32_e32 v164, v55
	v_add_f32_e32 v55, 1.0, v163
	v_rcp_f32_e32 v165, v55
	v_pk_mul_f32 v[156:157], v[156:157], v[138:139]
	v_cmp_le_f32_e32 vcc, 0, v75
	v_cmp_le_f32_e64 s[0:1], 0, v74
	v_mul_f32_e32 v77, v187, v186
	v_cndmask_b32_e32 v79, v157, v139, vcc
	v_cndmask_b32_e64 v78, v156, v138, s[0:1]
	v_cndmask_b32_e32 v189, v139, v157, vcc
	v_cndmask_b32_e64 v190, v138, v156, s[0:1]
	v_pk_mul_f32 v[138:139], v[162:163], v[164:165]
	v_cmp_le_f32_e32 vcc, 0, v160
	v_cmp_le_f32_e64 s[0:1], 0, v161
	v_mul_f32_e32 v72, v190, v189
	v_cndmask_b32_e32 v158, v164, v138, vcc
	v_cndmask_b32_e64 v76, v165, v139, s[0:1]
	v_cndmask_b32_e64 v75, v139, v165, s[0:1]
	v_cndmask_b32_e32 v74, v138, v164, vcc
	v_pk_mul_f32 v[138:139], v[158:159], v[76:77]
	v_mov_b64_e32 v[156:157], v[62:63]
	v_mov_b32_e32 v55, v139
	v_mov_b32_e32 v73, v139
	s_nop 1
	v_permlane32_swap_b32_e32 v55, v73
	v_cndmask_b32_e64 v73, v55, v73, s[6:7]
	v_pk_mul_f32 v[138:139], v[138:139], v[72:73]
	v_mul_f32_e64 v62, |v156|, s65
	v_mov_b32_e32 v55, v138
	v_mov_b32_e32 v72, v138
	s_nop 1
	v_permlane32_swap_b32_e32 v55, v72
	v_cndmask_b32_e64 v185, 1.0, v124, s[6:7]
	v_exp_f32_e32 v158, v62
	v_mul_f32_e64 v62, |v157|, s65
	v_cndmask_b32_e64 v124, v55, v72, s[6:7]
	v_mul_f32_e64 v55, |v60|, s65
	v_exp_f32_e32 v159, v62
	v_exp_f32_e32 v162, v55
	v_mul_f32_e64 v55, |v61|, s65
	v_exp_f32_e32 v163, v55
	v_add_f32_e32 v62, 1.0, v158
	v_rcp_f32_e32 v160, v62
	v_add_f32_e32 v62, 1.0, v159
	v_add_f32_e32 v55, 1.0, v162
	v_rcp_f32_e32 v161, v62
	v_rcp_f32_e32 v164, v55
	v_add_f32_e32 v55, 1.0, v163
	v_rcp_f32_e32 v165, v55
	v_pk_mul_f32 v[158:159], v[158:159], v[160:161]
	v_cmp_le_f32_e32 vcc, 0, v156
	v_cmp_le_f32_e64 s[0:1], 0, v157
	v_cndmask_b32_e32 v132, v160, v158, vcc
	v_cndmask_b32_e32 v156, v158, v160, vcc
	v_pk_mul_f32 v[162:163], v[162:163], v[164:165]
	v_cmp_le_f32_e32 vcc, 0, v60
	v_mul_f32_e64 v72, |v50|, s65
	v_cndmask_b32_e64 v157, v159, v161, s[0:1]
	v_cndmask_b32_e64 v158, v161, v159, s[0:1]
	v_cndmask_b32_e32 v60, v164, v162, vcc
	v_cmp_le_f32_e64 s[0:1], 0, v61
	v_cndmask_b32_e32 v166, v162, v164, vcc
	v_exp_f32_e32 v162, v72
	v_mul_f32_e64 v72, |v51|, s65
	v_cmp_le_f32_e32 vcc, 0, v50
	v_mul_f32_e64 v50, |v48|, s65
	v_cndmask_b32_e64 v167, v163, v165, s[0:1]
	v_cndmask_b32_e64 v130, v165, v163, s[0:1]
	v_exp_f32_e32 v163, v72
	v_exp_f32_e32 v170, v50
	v_mul_f32_e64 v50, |v49|, s65
	v_exp_f32_e32 v171, v50
	v_pk_mul_f32 v[62:63], v[138:139], v[124:125]
	v_add_f32_e32 v72, 1.0, v162
	v_pk_mul_f32 v[138:139], v[62:63], v[62:63] op_sel:[0,1] op_sel_hi:[1,0]
	v_mov_b32_e32 v61, v134
	v_mov_b32_e32 v159, v138
	v_rcp_f32_e32 v164, v72
	v_add_f32_e32 v72, 1.0, v163
	v_add_f32_e32 v50, 1.0, v170
	v_pk_mul_f32 v[160:161], v[132:133], v[158:159]
	v_pk_mul_f32 v[60:61], v[60:61], v[130:131]
	v_rcp_f32_e32 v165, v72
	v_rcp_f32_e32 v172, v50
	v_add_f32_e32 v50, 1.0, v171
	v_pk_mul_f32 v[60:61], v[60:61], v[160:161]
	v_rcp_f32_e32 v173, v50
	v_mov_b32_e32 v55, v60
	v_mov_b32_e32 v62, v60
	s_nop 1
	v_permlane32_swap_b32_e32 v55, v62
	v_cndmask_b32_e64 v62, v55, v62, s[6:7]
	v_pk_mul_f32 v[162:163], v[162:163], v[164:165]
	v_cmp_le_f32_e64 s[0:1], 0, v51
	v_mul_f32_e32 v55, v60, v62
	v_cndmask_b32_e32 v136, v164, v162, vcc
	v_cndmask_b32_e64 v51, v163, v165, s[0:1]
	v_cndmask_b32_e32 v50, v162, v164, vcc
	v_cndmask_b32_e64 v168, v165, v163, s[0:1]
	v_pk_mul_f32 v[164:165], v[170:171], v[172:173]
	v_cmp_le_f32_e32 vcc, 0, v48
	v_cmp_le_f32_e64 s[0:1], 0, v49
	v_mul_f32_e32 v169, v55, v61
	v_cndmask_b32_e32 v48, v172, v164, vcc
	v_cndmask_b32_e64 v134, v173, v165, s[0:1]
	v_mov_b32_e32 v49, v54
	v_pk_mul_f32 v[162:163], v[136:137], v[168:169]
	v_pk_mul_f32 v[48:49], v[48:49], v[134:135]
	v_cndmask_b32_e64 v171, v165, v173, s[0:1]
	v_cndmask_b32_e32 v170, v164, v172, vcc
	v_pk_mul_f32 v[164:165], v[48:49], v[162:163]
	v_cndmask_b32_e64 v126, 1.0, v135, s[6:7]
	v_mov_b32_e32 v48, v164
	v_mov_b32_e32 v49, v164
	s_nop 1
	v_permlane32_swap_b32_e32 v48, v49
	v_cndmask_b32_e64 v72, v48, v49, s[6:7]
	v_cndmask_b32_e64 v48, 1.0, v72, s[6:7]
	v_mul_f32_e32 v49, v48, v165
	v_mul_f32_e32 v48, v168, v49
	v_pk_mul_f32 v[54:55], v[50:51], v[48:49]
	v_mul_f32_e32 v49, v136, v48
	v_mul_f32_e32 v48, v134, v49
	v_pk_mul_f32 v[134:135], v[170:171], v[48:49]
	v_mul_f32_e32 v48, v126, v163
	v_mul_f32_e32 v77, v155, v48
	v_mul_f32_e32 v48, v53, v48
	v_mul_f32_e32 v126, v154, v48
	v_mul_f32_e32 v15, v15, v48
	v_cndmask_b32_e64 v48, 1.0, v62, s[6:7]
	v_mul_f32_e32 v49, v48, v61
	v_mul_f32_e32 v48, v158, v49
	v_pk_mul_f32 v[60:61], v[156:157], v[48:49]
	v_mul_f32_e32 v49, v132, v48
	v_cndmask_b32_e64 v184, 1.0, v131, s[6:7]
	v_mul_f32_e32 v48, v130, v49
	v_pk_mul_f32 v[130:131], v[166:167], v[48:49]
	v_mul_f32_e32 v48, v184, v161
	v_cndmask_b32_e64 v66, 1.0, v66, s[6:7]
	v_mul_f32_e32 v133, v153, v15
	v_mul_f32_e32 v15, v52, v15
	v_mul_f32_e32 v62, v179, v48
	v_mul_f32_e32 v48, v129, v48
	v_mul_f32_e32 v0, v0, v15
	v_mul_f32_e32 v15, v66, v169
	v_mul_f32_e32 v132, v178, v48
	v_mul_f32_e32 v48, v127, v48
	v_lshl_add_u32 v154, s17, 6, v152
	v_mul_f32_e32 v66, v177, v15
	v_mul_f32_e32 v15, v59, v15
	v_mul_f32_e32 v139, v56, v48
	v_mul_f32_e32 v153, v128, v48
	ds_read_b64_tr_b16 v[48:49], v154 offset:53248
	ds_read_b64_tr_b16 v[50:51], v154 offset:53760
	v_mul_f32_e32 v136, v176, v15
	v_mul_f32_e32 v15, v57, v15
	v_mul_f32_e32 v137, v175, v15
	v_mul_f32_e32 v15, v58, v15
	v_cvt_pk_bf16_f32 v53, v54, v55
	v_cvt_pk_bf16_f32 v55, v126, v77
	ds_read_b64_tr_b16 v[56:57], v154 offset:61440
	ds_read_b64_tr_b16 v[58:59], v154 offset:61952
	ds_read_b64_tr_b16 v[126:127], v154 offset:54272
	ds_read_b64_tr_b16 v[128:129], v154 offset:54784
	v_cvt_pk_bf16_f32 v52, v134, v135
	v_cvt_pk_bf16_f32 v54, v0, v133
	v_mul_f32_e32 v15, v174, v15
	v_mul_f32_e32 v0, v14, v153
	s_waitcnt lgkmcnt(4)
; template <int DQK, int MODE, bool QN, bool KN> ...
;     ...
;         for (int m = 0; m < 8; ++m) {
;           const int kb = m >> 2, g = m & 3;
;           float tq = sp[m] * (h == 0 ? cpo[m] : 1.f);
; #pragma unroll
;           for (int c = 3; c >= 0; --c) { sacc[kb][4 * g + c] = beta[kb][4 * g + c] * tq; tq *= ff[kb][4 * g + c]; }
;         }
;       } else if (fixed_shift) {
;         float ps = 0.f;
; #pragma unroll
;         for (int kb = 0; kb < 2; ++kb)
; #pragma unroll
;           for (int i = 0; i < 16; ++i) { const float pv = __builtin_amdgcn_exp2f(sacc[kb][i]); sacc[kb][i] = pv; ps += pv; }
;         l_run += ps;
;       } else {
;         float tmax = -INFINITY;
; #pragma unroll
;         for (int kb = 0; kb < 2; ++kb)
; #pragma unroll
;           for (int i = 0; i < 16; ++i) {
;             tmax = fmaxf(tmax, sacc[kb][i]);
;           }
;         tmax = fmaxf(tmax, __shfl_xor(tmax, 32));
;         const float m_new = fmaxf(m_run, tmax);
;         const float alpha = __builtin_amdgcn_exp2f(m_run - m_new);
;         m_run = m_new;
;         float ps = 0.f;
; #pragma unroll
;         for (int kb = 0; kb < 2; ++kb)
; #pragma unroll
;           for (int i = 0; i < 16; ++i) { const float pv = __builtin_amdgcn_exp2f(sacc[kb][i] - m_new); sacc[kb][i] = pv; ps += pv; }
;         l_run = l_run * alpha + ps;
;         if (__builtin_amdgcn_ballot_w64(alpha != 1.f) != 0) {
; #pragma unroll
;           for (int a = 0; a < 2; ++a)
; #pragma unroll
;             for (int i = 0; i < 16; ++i) o[a][i] *= alpha;
;         }
;       }
; #pragma unroll
;       for (int kb = 0; kb < 2; ++kb)
; #pragma unroll
;         for (int s2 = 0; s2 < 2; ++s2) {
;           u32x4 pw;
;           pw.x = pack2(sacc[kb][8 * s2 + 0], sacc[kb][8 * s2 + 1]); pw.y = pack2(sacc[kb][8 * s2 + 2], sacc[kb][8 * s2 + 3]);
;           pw.z = pack2(sacc[kb][8 * s2 + 4], sacc[kb][8 * s2 + 5]); pw.w = pack2(sacc[kb][8 * s2 + 6], sacc[kb][8 * s2 + 7]);
;           const bf16x8 pf = __builtin_bit_cast(bf16x8, pw);
; #pragma unroll
;           for (int dvb = 0; dvb < 2; ++dvb) {
;             const char* vb = sV + dvb * VIMG + (kb * 32 + 16 * s2) * 64 + vtr_off;
;             const s16x4 v0 = tr_read(vb), v1 = tr_read(vb + 8 * 64);
;             const bf16x8 vf = __builtin_shufflevector(v0, v1, 0, 1, 2, 3, 4, 5, 6, 7);
;             o[dvb] = MFMA32(vf, pf, o[dvb]);
;           }
	v_mfma_f32_32x32x16_bf16 v[32:47], v[48:51], v[52:55], v[32:47]
	ds_read_b64_tr_b16 v[48:49], v154 offset:62464
	ds_read_b64_tr_b16 v[50:51], v154 offset:62976
	v_mul_f32_e32 v14, v185, v138
	v_mul_f32_e32 v77, v183, v14
	v_mul_f32_e32 v14, v69, v14
	v_mul_f32_e32 v69, v182, v14
	v_mul_f32_e32 v14, v67, v14
	s_waitcnt lgkmcnt(4)
	v_mfma_f32_32x32x16_bf16 v[16:31], v[56:59], v[52:55], v[16:31]
	v_cvt_pk_bf16_f32 v52, v15, v137
	v_cvt_pk_bf16_f32 v53, v136, v66
	v_cvt_pk_bf16_f32 v54, v130, v131
	v_cvt_pk_bf16_f32 v55, v60, v61
	v_mul_f32_e32 v56, v181, v14
	v_mul_f32_e32 v14, v68, v14
	v_mul_f32_e32 v57, v180, v14
	s_waitcnt lgkmcnt(2)
	v_mfma_f32_32x32x16_bf16 v[32:47], v[126:129], v[52:55], v[32:47]
	v_cndmask_b32_e64 v14, 1.0, v124, s[6:7]
	v_mul_f32_e32 v15, v14, v63
	v_mul_f32_e32 v14, v189, v15
	v_mul_f32_e64 v66, v78, v14
	v_mul_f32_e64 v67, v79, v15
	v_mul_f32_e32 v15, v190, v14
	v_mul_f32_e32 v14, v76, v15
	v_pk_mul_f32 v[14:15], v[74:75], v[14:15]
	s_waitcnt lgkmcnt(0)
	v_mfma_f32_32x32x16_bf16 v[16:31], v[48:51], v[52:55], v[16:31]
	ds_read_b64_tr_b16 v[48:49], v154 offset:55296
	ds_read_b64_tr_b16 v[50:51], v154 offset:55808
	v_cvt_pk_bf16_f32 v53, v132, v62
	v_cvt_pk_bf16_f32 v54, v57, v56
	ds_read_b64_tr_b16 v[56:57], v154 offset:63488
	ds_read_b64_tr_b16 v[58:59], v154 offset:64000
	ds_read_b64_tr_b16 v[60:61], v154 offset:56320
	ds_read_b64_tr_b16 v[62:63], v154 offset:56832
	v_cvt_pk_bf16_f32 v52, v0, v139
	v_cvt_pk_bf16_f32 v55, v69, v77
	v_cndmask_b32_e64 v0, 1.0, v73, s[6:7]
	v_mul_f32_e32 v69, v125, v0
	s_waitcnt lgkmcnt(4)
	v_mfma_f32_32x32x16_bf16 v[32:47], v[48:51], v[52:55], v[32:47]
	v_mul_f32_e32 v68, v186, v69
	ds_read_b64_tr_b16 v[48:49], v154 offset:64512
	ds_read_b64_tr_b16 v[50:51], v154 offset:65024
	v_mul_f32_e64 v64, v64, v68
	v_mul_f32_e64 v65, v65, v69
	v_mul_f32_e32 v0, v164, v72
	v_mul_f32_e32 v125, v0, v165
	s_waitcnt lgkmcnt(4)
	v_mfma_f32_32x32x16_bf16 v[16:31], v[56:59], v[52:55], v[16:31]
	v_mul_f32_e32 v53, v187, v68
	v_mul_f32_e32 v52, v188, v53
	v_mul_f32_e64 v54, v70, v52
	v_mul_f32_e64 v55, v71, v53
	v_cvt_pk_bf16_f32 v52, v14, v15
	v_cvt_pk_bf16_f32 v53, v66, v67
	v_cvt_pk_bf16_f32 v54, v54, v55
	v_cvt_pk_bf16_f32 v55, v64, v65
	s_waitcnt lgkmcnt(2)
	s_nop 0
	v_mfma_f32_32x32x16_bf16 v[32:47], v[60:63], v[52:55], v[32:47]
	s_waitcnt lgkmcnt(0)
	v_mfma_f32_32x32x16_bf16 v[16:31], v[48:51], v[52:55], v[16:31]
